# v34 + weight conversion balanced against the adaLN GEMV: first 16560 items over all workgroups, the rest only on the 112 workgroups that have no GEMV work
# baseline (speedup 1.0000x reference)
; #define LAS __attribute__((address_space(3)))
; __device__ __forceinline__ void convert_weights(const PL& P, LAS unsigned char* lds, int gw, int NGW, int wave, int lane) {
;     LAS float* scr = (LAS float*)(lds + wave * 8448);
;     constexpr int IT_F = 1408, IT_FFN = 12 * IT_F, IT_QKV = 1536, IT_WO = 512, IT_WIN = 1024, IT_WOUT = 512;
;     constexpr int NITEMS = IT_FFN + IT_QKV + IT_WO + IT_WIN + IT_WOUT;
;     for (int it = gw; it < NITEMS; it += NGW) {
;         int r = it;
.LBB0_622:
	s_or_b64 exec, exec, s[0:1]
	s_cmpk_gt_i32 s8, 0x4fff
	s_cbranch_scc1 .LBB0_659
	v_lshlrev_b32_e32 v0, 2, v227
	v_and_b32_e32 v32, 28, v0
	v_lshlrev_b32_e32 v0, 3, v227
	s_mul_i32 s0, s48, 0x2100
	v_lshrrev_b32_e32 v33, 3, v227
	v_and_b32_e32 v34, 56, v0
	s_add_i32 s0, s0, 0
	v_mul_u32_u24_e32 v0, 0x84, v34
	v_lshlrev_b32_e32 v1, 2, v33
	v_lshl_add_u32 v35, v32, 2, s0
	v_mul_u32_u24_e32 v36, 0x84, v33
	v_or_b32_e32 v37, 8, v33
	v_or_b32_e32 v38, 16, v33
	v_or_b32_e32 v39, 24, v33
	v_add3_u32 v40, s0, v0, v1
	s_lshl_b32 s3, s8, 5
	s_lshl_b32 s9, s2, 5
	s_lshl_b32 s12, s8, 1
	s_lshl_b32 s13, s2, 1
	s_movk_i32 vcc_lo, 0x40b0
	v_writelane_b32 v250, vcc_lo, 61
	v_writelane_b32 v250, s2, 62
	s_movk_i32 vcc_lo, 0x5000
	s_cmpk_lt_u32 s5, 0x90
	s_cbranch_scc1 .Lcv_nop2
	s_add_i32 vcc_lo, s5, 0xffffff70
	s_lshl_b32 vcc_lo, vcc_lo, 3
	s_add_i32 vcc_lo, vcc_lo, s48
	s_addk_i32 vcc_lo, 0x40b0
.Lcv_nop2:
	v_writelane_b32 v250, vcc_lo, 60
	s_branch .LBB0_627

; __device__ __forceinline__ void convert_weights(const PL& P, LAS unsigned char* lds, int gw, int NGW, int wave, int lane) {
;     ...
;     for (int it = gw; it < NITEMS; it += NGW) {
;         int r = it;
.LBB0_626:
	s_add_i32 s8, s8, s2
	s_add_i32 s3, s3, s9
	s_add_i32 s12, s12, s13
	v_readlane_b32 vcc_lo, v250, 61
	s_nop 0
	s_cmp_lt_i32 s8, vcc_lo
	s_cbranch_scc1 .LBB0_627
	s_cmpk_eq_i32 vcc_lo, 0x5000
	s_cbranch_scc1 .Lcv_done
	v_readlane_b32 s8, v250, 60
	s_movk_i32 s2, 0x380
	s_nop 0
	s_lshl_b32 s3, s8, 5
	s_lshl_b32 s9, s2, 5
	s_lshl_b32 s12, s8, 1
	s_lshl_b32 s13, s2, 1
	s_movk_i32 vcc_lo, 0x5000
	v_writelane_b32 v250, vcc_lo, 61
	s_cmpk_lt_i32 s8, 0x5000
	s_cbranch_scc1 .LBB0_627
.Lcv_done:
	v_readlane_b32 s2, v250, 62
	s_nop 0
	s_branch .LBB0_659
